# on v76: non-temporal hint also on the LayerNorm epilogues' read-once residual loads (P3 and P5)
# baseline (speedup 1.0000x reference)
.LBB0_781:
	s_add_u32 s88, s8, 0x7200000
	s_addc_u32 s89, s9, 0
	s_lshl_b32 s8, s46, 6
	v_readlane_b32 s13, v245, 56
	v_ashrrev_i32_e32 v0, 1, v240
	s_lshl_b32 s9, s56, 5
	s_or_b32 s68, s13, s8
	v_readlane_b32 s8, v245, 60
	v_and_b32_e32 v0, -8, v0
	s_add_i32 s8, s8, s9
	s_lshl_b32 s13, s68, 8
	v_add_u32_e32 v202, s8, v0
	v_add_u32_e32 v200, s13, v239
	v_ashrrev_i32_e32 v203, 31, v202
	v_ashrrev_i32_e32 v201, 31, v200
	v_lshl_add_u64 v[82:83], v[202:203], 1, s[88:89]
	v_lshlrev_b64 v[204:205], 11, v[200:201]
	v_lshl_add_u64 v[84:85], v[82:83], 0, v[204:205]
	s_barrier
	global_load_dwordx4 v[206:209], v[84:85], off nt
	global_load_dwordx4 v[186:189], v[84:85], off offset:256 nt
	v_or_b32_e32 v84, 16, v200
	v_ashrrev_i32_e32 v85, 31, v84
	v_lshlrev_b64 v[84:85], 11, v[84:85]
	v_lshl_add_u64 v[84:85], v[82:83], 0, v[84:85]
	global_load_dwordx4 v[182:185], v[84:85], off nt
	global_load_dwordx4 v[178:181], v[84:85], off offset:256 nt
	v_or_b32_e32 v84, 32, v200
	v_ashrrev_i32_e32 v85, 31, v84
	v_lshlrev_b64 v[84:85], 11, v[84:85]
	v_lshl_add_u64 v[84:85], v[82:83], 0, v[84:85]
	global_load_dwordx4 v[174:177], v[84:85], off nt
	global_load_dwordx4 v[170:173], v[84:85], off offset:256 nt
	v_or_b32_e32 v84, 48, v200
	v_ashrrev_i32_e32 v85, 31, v84
	v_lshlrev_b64 v[84:85], 11, v[84:85]
	v_lshl_add_u64 v[84:85], v[82:83], 0, v[84:85]
	global_load_dwordx4 v[166:169], v[84:85], off nt
	global_load_dwordx4 v[162:165], v[84:85], off offset:256 nt
	v_add_u32_e32 v84, 0x80, v200
	v_ashrrev_i32_e32 v85, 31, v84
	v_lshlrev_b64 v[198:199], 11, v[84:85]
	v_lshl_add_u64 v[84:85], v[82:83], 0, v[198:199]
	global_load_dwordx4 v[158:161], v[84:85], off nt
	global_load_dwordx4 v[154:157], v[84:85], off offset:256 nt
	v_add_u32_e32 v84, 0x90, v200
	v_ashrrev_i32_e32 v85, 31, v84
	v_lshlrev_b64 v[196:197], 11, v[84:85]
	v_lshl_add_u64 v[84:85], v[82:83], 0, v[196:197]
	global_load_dwordx4 v[150:153], v[84:85], off nt
	global_load_dwordx4 v[146:149], v[84:85], off offset:256 nt
	v_add_u32_e32 v84, 0xa0, v200
	v_ashrrev_i32_e32 v85, 31, v84
	v_lshlrev_b64 v[194:195], 11, v[84:85]
	v_lshl_add_u64 v[84:85], v[82:83], 0, v[194:195]
	global_load_dwordx4 v[110:113], v[84:85], off nt
	global_load_dwordx4 v[106:109], v[84:85], off offset:256 nt
	v_add_u32_e32 v84, 0xb0, v200
	v_ashrrev_i32_e32 v85, 31, v84
	v_lshlrev_b64 v[192:193], 11, v[84:85]
	v_lshl_add_u64 v[82:83], v[82:83], 0, v[192:193]
	v_lshl_add_u64 v[216:217], v[202:203], 2, s[74:75]
	global_load_dwordx4 v[86:89], v[82:83], off nt
	s_nop 0
	global_load_dwordx4 v[82:85], v[82:83], off offset:256 nt
	s_lshl_b32 s8, s56, 3
	s_add_i32 s46, s8, 0
	v_cmp_gt_u32_e32 vcc, 16, v240
	s_waitcnt vmcnt(0)
	v_lshlrev_b32_e32 v210, 16, v206
	v_and_b32_e32 v211, 0xffff0000, v206
	v_lshlrev_b32_e32 v206, 16, v207
	v_and_b32_e32 v207, 0xffff0000, v207
	v_lshlrev_b32_e32 v212, 16, v208
	v_and_b32_e32 v213, 0xffff0000, v208
	v_lshlrev_b32_e32 v208, 16, v209
	v_and_b32_e32 v209, 0xffff0000, v209
	v_pk_fma_f32 v[210:211], v[210:211], s[66:67], v[126:127] op_sel_hi:[1,0,1]
	v_pk_fma_f32 v[206:207], v[206:207], s[66:67], v[128:129] op_sel_hi:[1,0,1]
	v_pk_fma_f32 v[214:215], v[212:213], s[66:67], v[118:119] op_sel_hi:[1,0,1]
	v_pk_fma_f32 v[208:209], v[208:209], s[66:67], v[120:121] op_sel_hi:[1,0,1]
	global_load_dwordx4 v[118:121], v[216:217], off offset:16
	global_load_dwordx4 v[126:129], v[216:217], off
	v_lshlrev_b32_e32 v218, 16, v188
	v_and_b32_e32 v219, 0xffff0000, v188
	v_lshlrev_b32_e32 v242, 16, v189
	v_and_b32_e32 v243, 0xffff0000, v189
	s_waitcnt vmcnt(1)
	v_pk_add_f32 v[208:209], v[120:121], v[208:209]
	s_waitcnt vmcnt(0)
	v_pk_add_f32 v[212:213], v[128:129], v[206:207]
	v_pk_add_f32 v[206:207], v[118:119], v[214:215]
	v_lshlrev_b32_e32 v214, 16, v186
	v_and_b32_e32 v215, 0xffff0000, v186
	v_lshlrev_b32_e32 v186, 16, v187
	v_and_b32_e32 v187, 0xffff0000, v187
	v_pk_fma_f32 v[188:189], v[214:215], s[66:67], v[142:143] op_sel_hi:[1,0,1]
	v_pk_fma_f32 v[214:215], v[186:187], s[66:67], v[144:145] op_sel_hi:[1,0,1]
	v_pk_fma_f32 v[186:187], v[218:219], s[66:67], v[114:115] op_sel_hi:[1,0,1]
	v_pk_fma_f32 v[218:219], v[242:243], s[66:67], v[116:117] op_sel_hi:[1,0,1]
	global_load_dwordx4 v[114:117], v[216:217], off offset:528
	global_load_dwordx4 v[142:145], v[216:217], off offset:512
	v_pk_add_f32 v[210:211], v[126:127], v[210:211]
	v_add_f32_e32 v201, v212, v213
	v_add_f32_e32 v0, v210, v211
	v_add_f32_e32 v0, v0, v201
	v_add_f32_e32 v201, v206, v207
	v_add_f32_e32 v0, 0, v0
	s_waitcnt vmcnt(1)
	v_pk_add_f32 v[186:187], v[186:187], v[114:115]
	s_waitcnt vmcnt(0)
	v_pk_add_f32 v[216:217], v[214:215], v[144:145]
	v_pk_add_f32 v[214:215], v[188:189], v[142:143]
	v_pk_add_f32 v[188:189], v[218:219], v[116:117]
	v_add_f32_e32 v218, v208, v209
	v_add_f32_e32 v201, v201, v218
	v_add_f32_e32 v0, v201, v0
	v_add_f32_e32 v201, v214, v215
	v_add_f32_e32 v218, v216, v217
	v_add_f32_e32 v201, v201, v218
	v_add_f32_e32 v0, v201, v0
	v_add_f32_e32 v201, v186, v187
	v_add_f32_e32 v218, v188, v189
	v_add_f32_e32 v201, v201, v218
	v_add_f32_e32 v0, v201, v0
	v_mov_b32_e32 v201, v0
	s_nop 1
	v_permlane16_swap_b32_e32 v0, v201
	s_nop 0
	v_add_f32_e32 v0, v0, v201
	v_mov_b32_e32 v201, v0
	s_nop 1
	v_permlane32_swap_b32_e32 v0, v201
	s_nop 0
	v_add_f32_e32 v0, v0, v201
	v_fmamk_f32 v218, v0, 0xbc800000, v213
	v_fmamk_f32 v241, v0, 0xbc800000, v211
	v_fmamk_f32 v201, v0, 0xbc800000, v212
	v_fmamk_f32 v219, v0, 0xbc800000, v210
	v_mul_f32_e32 v241, v241, v241
	v_mul_f32_e32 v218, v218, v218
	v_fmac_f32_e32 v241, v219, v219
	v_fmac_f32_e32 v218, v201, v201
	v_fmamk_f32 v219, v0, 0xbc800000, v209
	v_fmamk_f32 v242, v0, 0xbc800000, v207
	v_add_f32_e32 v201, v241, v218
	v_fmamk_f32 v218, v0, 0xbc800000, v208
	v_fmamk_f32 v241, v0, 0xbc800000, v206
	v_mul_f32_e32 v242, v242, v242
	v_mul_f32_e32 v219, v219, v219
	v_fmac_f32_e32 v242, v241, v241
	v_fmac_f32_e32 v219, v218, v218
	v_add_f32_e32 v218, v242, v219
	v_fmamk_f32 v219, v0, 0xbc800000, v217
	v_fmamk_f32 v242, v0, 0xbc800000, v215
	v_add_f32_e32 v201, v201, v218
	v_fmamk_f32 v218, v0, 0xbc800000, v216
	v_fmamk_f32 v241, v0, 0xbc800000, v214
	v_mul_f32_e32 v242, v242, v242
	v_mul_f32_e32 v219, v219, v219
	v_fmac_f32_e32 v242, v241, v241
	v_fmac_f32_e32 v219, v218, v218
	v_add_f32_e32 v218, v242, v219
	v_fmamk_f32 v219, v0, 0xbc800000, v189
	v_fmamk_f32 v242, v0, 0xbc800000, v187
	v_add_f32_e32 v201, v218, v201
	v_fmamk_f32 v218, v0, 0xbc800000, v188
	v_fmamk_f32 v241, v0, 0xbc800000, v186
	v_mul_f32_e32 v242, v242, v242
	v_mul_f32_e32 v219, v219, v219
	v_fmac_f32_e32 v242, v241, v241
	v_fmac_f32_e32 v219, v218, v218
	v_add_f32_e32 v218, v242, v219
	v_add_f32_e32 v201, v218, v201
	v_mov_b32_e32 v218, v201
	s_nop 1
	v_permlane16_swap_b32_e32 v201, v218
	s_nop 0
	v_add_f32_e32 v201, v201, v218
	v_mov_b32_e32 v218, v201
	s_nop 1
	v_permlane32_swap_b32_e32 v201, v218
	s_and_saveexec_b64 s[8:9], vcc
	s_cbranch_execz .LBB0_783
	s_lshl_b32 s55, s12, 11
	s_add_i32 s55, s46, s55
	v_mul_f32_e32 v242, 0x3c800000, v0
	v_lshl_add_u32 v0, v240, 5, s55
	v_add_f32_e32 v243, v201, v218
	ds_write_b64 v0, v[242:243]

.LBB0_953:
	s_lshl_b32 s46, s56, 6
	v_readlane_b32 s56, v245, 56
	v_ashrrev_i32_e32 v0, 1, v209
	s_lshl_b32 s55, s13, 5
	s_or_b32 s69, s56, s46
	v_readlane_b32 s46, v245, 60
	v_and_b32_e32 v0, -8, v0
	s_add_i32 s46, s46, s55
	v_add_u32_e32 v188, s46, v0
	s_lshl_b32 s68, s69, 8
	v_add_u32_e32 v200, s68, v208
	v_ashrrev_i32_e32 v189, 31, v188
	v_lshl_add_u64 v[82:83], v[188:189], 1, s[8:9]
	s_mov_b64 s[8:9], 0x7200000
	v_ashrrev_i32_e32 v201, 31, v200
	v_lshl_add_u64 v[186:187], v[82:83], 0, s[8:9]
	v_lshlrev_b64 v[82:83], 11, v[200:201]
	v_lshl_add_u64 v[82:83], v[186:187], 0, v[82:83]
	s_barrier
	global_load_dwordx4 v[202:205], v[82:83], off nt
	global_load_dwordx4 v[210:213], v[82:83], off offset:256 nt
	v_or_b32_e32 v82, 16, v200
	v_ashrrev_i32_e32 v83, 31, v82
	v_lshlrev_b64 v[82:83], 11, v[82:83]
	v_lshl_add_u64 v[82:83], v[186:187], 0, v[82:83]
	global_load_dwordx4 v[174:177], v[82:83], off nt
	global_load_dwordx4 v[170:173], v[82:83], off offset:256 nt
	v_or_b32_e32 v82, 32, v200
	v_ashrrev_i32_e32 v83, 31, v82
	v_lshlrev_b64 v[82:83], 11, v[82:83]
	v_lshl_add_u64 v[82:83], v[186:187], 0, v[82:83]
	global_load_dwordx4 v[158:161], v[82:83], off nt
	global_load_dwordx4 v[154:157], v[82:83], off offset:256 nt
	v_or_b32_e32 v82, 48, v200
	v_ashrrev_i32_e32 v83, 31, v82
	v_lshlrev_b64 v[82:83], 11, v[82:83]
	v_add_u32_e32 v198, 0x80, v200
	v_lshl_add_u64 v[82:83], v[186:187], 0, v[82:83]
	v_ashrrev_i32_e32 v199, 31, v198
	global_load_dwordx4 v[150:153], v[82:83], off nt
	global_load_dwordx4 v[146:149], v[82:83], off offset:256 nt
	v_lshlrev_b64 v[82:83], 11, v[198:199]
	v_add_u32_e32 v196, 0x90, v200
	v_lshl_add_u64 v[82:83], v[186:187], 0, v[82:83]
	v_ashrrev_i32_e32 v197, 31, v196
	global_load_dwordx4 v[142:145], v[82:83], off nt
	global_load_dwordx4 v[138:141], v[82:83], off offset:256 nt
	v_lshlrev_b64 v[82:83], 11, v[196:197]
	v_add_u32_e32 v194, 0xa0, v200
	v_lshl_add_u64 v[82:83], v[186:187], 0, v[82:83]
	v_ashrrev_i32_e32 v195, 31, v194
	global_load_dwordx4 v[134:137], v[82:83], off nt
	global_load_dwordx4 v[130:133], v[82:83], off offset:256 nt
	v_lshlrev_b64 v[82:83], 11, v[194:195]
	v_add_u32_e32 v192, 0xb0, v200
	v_lshl_add_u64 v[82:83], v[186:187], 0, v[82:83]
	v_ashrrev_i32_e32 v193, 31, v192
	global_load_dwordx4 v[110:113], v[82:83], off nt
	global_load_dwordx4 v[106:109], v[82:83], off offset:256 nt
	v_lshlrev_b64 v[82:83], 11, v[192:193]
	v_lshl_add_u64 v[82:83], v[186:187], 0, v[82:83]
	global_load_dwordx4 v[90:93], v[82:83], off nt
	s_nop 0
	global_load_dwordx4 v[82:85], v[82:83], off offset:256 nt
	s_lshl_b32 s8, s13, 3
	s_add_i32 s13, s8, 0
	v_cmp_gt_u32_e32 vcc, 16, v209
	s_waitcnt vmcnt(0)
	v_lshlrev_b32_e32 v206, 16, v202
	v_and_b32_e32 v207, 0xffff0000, v202
	v_lshlrev_b32_e32 v214, 16, v203
	v_and_b32_e32 v215, 0xffff0000, v203
	v_lshlrev_b32_e32 v216, 16, v204
	v_and_b32_e32 v217, 0xffff0000, v204
	v_lshlrev_b32_e32 v204, 16, v205
	v_and_b32_e32 v205, 0xffff0000, v205
	v_pk_fma_f32 v[202:203], v[206:207], s[66:67], v[182:183] op_sel_hi:[1,0,1]
	v_pk_fma_f32 v[184:185], v[214:215], s[66:67], v[184:185] op_sel_hi:[1,0,1]
	v_pk_fma_f32 v[182:183], v[216:217], s[66:67], v[178:179] op_sel_hi:[1,0,1]
	v_pk_fma_f32 v[180:181], v[204:205], s[66:67], v[180:181] op_sel_hi:[1,0,1]
	v_lshlrev_b32_e32 v178, 16, v210
	v_and_b32_e32 v179, 0xffff0000, v210
	v_lshlrev_b32_e32 v204, 16, v211
	v_and_b32_e32 v205, 0xffff0000, v211
	v_lshlrev_b32_e32 v206, 16, v212
	v_and_b32_e32 v207, 0xffff0000, v212
	v_lshlrev_b32_e32 v210, 16, v213
	v_and_b32_e32 v211, 0xffff0000, v213
	v_pk_fma_f32 v[178:179], v[178:179], s[66:67], v[166:167] op_sel_hi:[1,0,1]
	v_pk_fma_f32 v[166:167], v[206:207], s[66:67], v[162:163] op_sel_hi:[1,0,1]
	v_pk_fma_f32 v[162:163], v[210:211], s[66:67], v[164:165] op_sel_hi:[1,0,1]
	v_add_f32_e32 v0, v202, v203
	v_add_f32_e32 v164, v184, v185
	v_add_f32_e32 v0, v0, v164
	v_add_f32_e32 v164, v182, v183
	v_add_f32_e32 v165, v180, v181
	v_pk_fma_f32 v[168:169], v[204:205], s[66:67], v[168:169] op_sel_hi:[1,0,1]
	v_add_f32_e32 v0, 0, v0
	v_add_f32_e32 v164, v164, v165
	v_add_f32_e32 v0, v164, v0
	v_add_f32_e32 v164, v178, v179
	v_add_f32_e32 v165, v168, v169
	v_add_f32_e32 v164, v164, v165
	v_add_f32_e32 v0, v164, v0
	v_add_f32_e32 v164, v166, v167
	v_add_f32_e32 v165, v162, v163
	v_add_f32_e32 v164, v164, v165
	v_add_f32_e32 v0, v164, v0
	v_mov_b32_e32 v164, v0
	s_nop 1
	v_permlane16_swap_b32_e32 v0, v164
	s_nop 0
	v_add_f32_e32 v0, v0, v164
	v_mov_b32_e32 v164, v0
	s_nop 1
	v_permlane32_swap_b32_e32 v0, v164
	s_nop 0
	v_add_f32_e32 v0, v0, v164
	v_fmamk_f32 v165, v0, 0xbc800000, v185
	v_fmamk_f32 v205, v0, 0xbc800000, v203
	v_fmamk_f32 v164, v0, 0xbc800000, v184
	v_fmamk_f32 v204, v0, 0xbc800000, v202
	v_mul_f32_e32 v205, v205, v205
	v_mul_f32_e32 v165, v165, v165
	v_fmac_f32_e32 v205, v204, v204
	v_fmac_f32_e32 v165, v164, v164
	v_fmamk_f32 v204, v0, 0xbc800000, v181
	v_fmamk_f32 v206, v0, 0xbc800000, v183
	v_add_f32_e32 v164, v205, v165
	v_fmamk_f32 v165, v0, 0xbc800000, v180
	v_fmamk_f32 v205, v0, 0xbc800000, v182
	v_mul_f32_e32 v206, v206, v206
	v_mul_f32_e32 v204, v204, v204
	v_fmac_f32_e32 v206, v205, v205
	v_fmac_f32_e32 v204, v165, v165
	v_add_f32_e32 v165, v206, v204
	v_fmamk_f32 v204, v0, 0xbc800000, v169
	v_fmamk_f32 v206, v0, 0xbc800000, v179
	v_add_f32_e32 v164, v164, v165
	v_fmamk_f32 v165, v0, 0xbc800000, v168
	v_fmamk_f32 v205, v0, 0xbc800000, v178
	v_mul_f32_e32 v206, v206, v206
	v_mul_f32_e32 v204, v204, v204
	v_fmac_f32_e32 v206, v205, v205
	v_fmac_f32_e32 v204, v165, v165
	v_add_f32_e32 v165, v206, v204
	v_fmamk_f32 v204, v0, 0xbc800000, v163
	v_fmamk_f32 v206, v0, 0xbc800000, v167
	v_add_f32_e32 v164, v165, v164
	v_fmamk_f32 v165, v0, 0xbc800000, v162
	v_fmamk_f32 v205, v0, 0xbc800000, v166
	v_mul_f32_e32 v206, v206, v206
	v_mul_f32_e32 v204, v204, v204
	v_fmac_f32_e32 v206, v205, v205
	v_fmac_f32_e32 v204, v165, v165
	v_add_f32_e32 v165, v206, v204
	v_add_f32_e32 v164, v165, v164
	v_mov_b32_e32 v165, v164
	s_nop 1
	v_permlane16_swap_b32_e32 v164, v165
	s_nop 0
	v_add_f32_e32 v164, v164, v165
	v_mov_b32_e32 v165, v164
	s_nop 1
	v_permlane32_swap_b32_e32 v164, v165
	s_and_saveexec_b64 s[8:9], vcc
	v_readlane_b32 s90, v244, 26
	s_cbranch_execz .LBB0_955
	s_lshl_b32 s46, s12, 11
	s_add_i32 s46, s13, s46
	v_mul_f32_e32 v204, 0x3c800000, v0
	v_lshl_add_u32 v0, v209, 5, s46
	v_add_f32_e32 v205, v164, v165
	ds_write_b64 v0, v[204:205]
